# MLA loop: group-B Q fragment LDS reads requested before the end-of-iteration barrier; K fragments lead the post-barrier LDS queue
# baseline (speedup 1.0000x reference)
.LBB0_738:
	s_waitcnt lgkmcnt(0)
	s_lshl_b32 s0, s8, 7
	v_readlane_b32 s6, v254, 11
	v_readlane_b32 s7, v254, 12
	s_add_u32 s6, s6, s0
	s_addc_u32 s7, s7, 0
	v_readlane_b32 s8, v254, 40
	ds_bpermute_b32 v8, v189, v0
	v_readlane_b32 s9, v254, 41
	s_add_u32 s0, s8, s0
	s_addc_u32 s1, s9, 0
	s_lshl_b32 s8, s3, 8
	s_addk_i32 s8, 0x3800
	s_lshl_b32 s3, s3, 11
	s_movk_i32 s9, 0x800
	v_cmp_gt_i32_e32 vcc, s9, v188
	v_mov_b32_e32 v10, s8
	v_mov_b32_e32 v11, s3
	v_cndmask_b32_e32 v2, v10, v11, vcc
	s_waitcnt lgkmcnt(0)
	v_add_f32_e32 v0, v0, v8
	v_add_u32_e32 v4, v2, v188
	v_mov_b64_e32 v[2:3], s[6:7]
	v_div_scale_f32 v8, s[6:7], v0, v0, 1.0
	v_rcp_f32_e32 v9, v8
	s_movk_i32 s3, 0x1040
	v_mad_i64_i32 v[6:7], s[6:7], v4, s3, v[2:3]
	v_fma_f32 v12, -v8, v9, 1.0
	v_fmac_f32_e32 v9, v12, v9
	v_div_scale_f32 v12, vcc, 1.0, v0, 1.0
	v_mul_f32_e32 v13, v12, v9
	v_fma_f32 v14, -v8, v13, v12
	v_fmac_f32_e32 v13, v14, v9
	v_fma_f32 v8, -v8, v13, v12
	v_mov_b32_e32 v191, v1
	v_div_fmas_f32 v8, v8, v9, v13
	v_lshl_add_u64 v[6:7], v[6:7], 0, v[190:191]
	v_div_fixup_f32 v0, v8, v0, 1.0
	global_load_dwordx2 v[8:9], v[6:7], off
	v_pk_mul_f32 v[14:15], v[64:65], v[0:1] op_sel_hi:[1,0]
	v_ashrrev_i32_e32 v5, 31, v4
	v_lshlrev_b64 v[4:5], 11, v[4:5]
	v_lshl_add_u64 v[4:5], s[0:1], 0, v[4:5]
	v_lshl_add_u64 v[4:5], v[4:5], 0, v[190:191]
	s_waitcnt vmcnt(0)
	v_lshlrev_b32_e32 v80, 16, v8
	v_and_b32_e32 v8, 0xffff0000, v8
	v_mul_f32_e32 v12, 0xbfb8aa3b, v80
	v_mul_f32_e32 v13, 0xbfb8aa3b, v8
	v_exp_f32_e32 v12, v12
	v_exp_f32_e32 v13, v13
	s_nop 0
	v_pk_add_f32 v[12:13], v[12:13], 1.0 op_sel_hi:[1,0]
	s_nop 0
	v_div_scale_f32 v64, s[6:7], v13, v13, v8
	v_rcp_f32_e32 v65, v64
	s_nop 0
	v_fma_f32 v81, -v64, v65, 1.0
	v_fmac_f32_e32 v65, v81, v65
	v_div_scale_f32 v81, vcc, v8, v13, v8
	v_mul_f32_e32 v82, v81, v65
	v_fma_f32 v83, -v64, v82, v81
	v_fmac_f32_e32 v82, v83, v65
	v_fma_f32 v64, -v64, v82, v81
	v_div_fmas_f32 v64, v64, v65, v82
	v_div_fixup_f32 v13, v64, v13, v8
	v_div_scale_f32 v8, s[6:7], v12, v12, v80
	v_rcp_f32_e32 v64, v8
	s_nop 0
	v_fma_f32 v65, -v8, v64, 1.0
	v_fmac_f32_e32 v64, v65, v64
	v_div_scale_f32 v65, vcc, v80, v12, v80
	v_mul_f32_e32 v81, v65, v64
	v_fma_f32 v82, -v8, v81, v65
	v_fmac_f32_e32 v81, v82, v64
	v_fma_f32 v8, -v8, v81, v65
	v_div_fmas_f32 v8, v8, v64, v81
	v_lshlrev_b32_e32 v64, 16, v9
	v_and_b32_e32 v65, 0xffff0000, v9
	v_div_fixup_f32 v12, v8, v12, v80
	v_mul_f32_e32 v8, 0xbfb8aa3b, v64
	v_mul_f32_e32 v9, 0xbfb8aa3b, v65
	v_exp_f32_e32 v8, v8
	v_exp_f32_e32 v9, v9
	v_pk_mul_f32 v[12:13], v[14:15], v[12:13]
	v_pk_mul_f32 v[14:15], v[66:67], v[0:1] op_sel_hi:[1,0]
	v_cvt_pk_bf16_f32 v12, v12, v13
	v_pk_add_f32 v[8:9], v[8:9], 1.0 op_sel_hi:[1,0]
	s_nop 0
	v_div_scale_f32 v66, s[6:7], v9, v9, v65
	v_rcp_f32_e32 v67, v66
	s_nop 0
	v_fma_f32 v80, -v66, v67, 1.0
	v_fmac_f32_e32 v67, v80, v67
	v_div_scale_f32 v80, vcc, v65, v9, v65
	v_mul_f32_e32 v81, v80, v67
	v_fma_f32 v82, -v66, v81, v80
	v_fmac_f32_e32 v81, v82, v67
	v_fma_f32 v66, -v66, v81, v80
	v_div_fmas_f32 v66, v66, v67, v81
	v_div_fixup_f32 v9, v66, v9, v65
	v_div_scale_f32 v65, s[6:7], v8, v8, v64
	v_rcp_f32_e32 v66, v65
	s_nop 0
	v_fma_f32 v67, -v65, v66, 1.0
	v_fmac_f32_e32 v66, v67, v66
	v_div_scale_f32 v67, vcc, v64, v8, v64
	v_mul_f32_e32 v80, v67, v66
	v_fma_f32 v81, -v65, v80, v67
	v_fmac_f32_e32 v80, v81, v66
	v_fma_f32 v65, -v65, v80, v67
	v_div_fmas_f32 v65, v65, v66, v80
	v_div_fixup_f32 v8, v65, v8, v64
	v_pk_mul_f32 v[8:9], v[14:15], v[8:9]
	v_pk_mul_f32 v[14:15], v[68:69], v[0:1] op_sel_hi:[1,0]
	v_cvt_pk_bf16_f32 v13, v8, v9
	global_load_dwordx2 v[8:9], v[6:7], off offset:16
	s_waitcnt vmcnt(0)
	v_lshlrev_b32_e32 v64, 16, v8
	v_and_b32_e32 v8, 0xffff0000, v8
	global_store_dwordx2 v[4:5], v[12:13], off
	v_mul_f32_e32 v12, 0xbfb8aa3b, v64
	v_mul_f32_e32 v13, 0xbfb8aa3b, v8
	v_exp_f32_e32 v12, v12
	v_exp_f32_e32 v13, v13
	s_nop 0
	v_pk_add_f32 v[12:13], v[12:13], 1.0 op_sel_hi:[1,0]
	s_nop 0
	v_div_scale_f32 v65, s[6:7], v13, v13, v8
	v_rcp_f32_e32 v66, v65
	s_nop 0
	v_fma_f32 v67, -v65, v66, 1.0
	v_fmac_f32_e32 v66, v67, v66
	v_div_scale_f32 v67, vcc, v8, v13, v8
	v_mul_f32_e32 v68, v67, v66
	v_fma_f32 v69, -v65, v68, v67
	v_fmac_f32_e32 v68, v69, v66
	v_fma_f32 v65, -v65, v68, v67
	v_div_fmas_f32 v65, v65, v66, v68
	v_div_fixup_f32 v13, v65, v13, v8
	v_div_scale_f32 v8, s[6:7], v12, v12, v64
	v_rcp_f32_e32 v65, v8
	s_nop 0
	v_fma_f32 v66, -v8, v65, 1.0
	v_fmac_f32_e32 v65, v66, v65
	v_div_scale_f32 v66, vcc, v64, v12, v64
	v_mul_f32_e32 v67, v66, v65
	v_fma_f32 v68, -v8, v67, v66
	v_fmac_f32_e32 v67, v68, v65
	v_fma_f32 v8, -v8, v67, v66
	v_div_fmas_f32 v8, v8, v65, v67
	v_div_fixup_f32 v12, v8, v12, v64
	v_lshlrev_b32_e32 v64, 16, v9
	v_and_b32_e32 v65, 0xffff0000, v9
	v_mul_f32_e32 v8, 0xbfb8aa3b, v64
	v_mul_f32_e32 v9, 0xbfb8aa3b, v65
	v_exp_f32_e32 v8, v8
	v_exp_f32_e32 v9, v9
	v_pk_mul_f32 v[12:13], v[14:15], v[12:13]
	v_pk_mul_f32 v[14:15], v[70:71], v[0:1] op_sel_hi:[1,0]
	v_cvt_pk_bf16_f32 v12, v12, v13
	v_pk_add_f32 v[8:9], v[8:9], 1.0 op_sel_hi:[1,0]
	s_nop 0
	v_div_scale_f32 v66, s[6:7], v9, v9, v65
	v_rcp_f32_e32 v67, v66
	s_nop 0
	v_fma_f32 v68, -v66, v67, 1.0
	v_fmac_f32_e32 v67, v68, v67
	v_div_scale_f32 v68, vcc, v65, v9, v65
	v_mul_f32_e32 v69, v68, v67
	v_fma_f32 v70, -v66, v69, v68
	v_fmac_f32_e32 v69, v70, v67
	v_fma_f32 v66, -v66, v69, v68
	v_div_fmas_f32 v66, v66, v67, v69
	v_div_fixup_f32 v9, v66, v9, v65
	v_div_scale_f32 v65, s[6:7], v8, v8, v64
	v_rcp_f32_e32 v66, v65
	s_nop 0
	v_fma_f32 v67, -v65, v66, 1.0
	v_fmac_f32_e32 v66, v67, v66
	v_div_scale_f32 v67, vcc, v64, v8, v64
	v_mul_f32_e32 v68, v67, v66
	v_fma_f32 v69, -v65, v68, v67
	v_fmac_f32_e32 v68, v69, v66
	v_fma_f32 v65, -v65, v68, v67
	v_div_fmas_f32 v65, v65, v66, v68
	v_div_fixup_f32 v8, v65, v8, v64
	v_pk_mul_f32 v[8:9], v[14:15], v[8:9]
	v_pk_mul_f32 v[14:15], v[72:73], v[0:1] op_sel_hi:[1,0]
	v_cvt_pk_bf16_f32 v13, v8, v9
	global_load_dwordx2 v[8:9], v[6:7], off offset:32
	s_waitcnt vmcnt(0)
	v_lshlrev_b32_e32 v64, 16, v8
	v_and_b32_e32 v8, 0xffff0000, v8
	global_store_dwordx2 v[4:5], v[12:13], off offset:16
	v_mul_f32_e32 v12, 0xbfb8aa3b, v64
	v_mul_f32_e32 v13, 0xbfb8aa3b, v8
	v_exp_f32_e32 v12, v12
	v_exp_f32_e32 v13, v13
	s_nop 0
	v_pk_add_f32 v[12:13], v[12:13], 1.0 op_sel_hi:[1,0]
	s_nop 0
	v_div_scale_f32 v65, s[6:7], v13, v13, v8
	v_rcp_f32_e32 v66, v65
	s_nop 0
	v_fma_f32 v67, -v65, v66, 1.0
	v_fmac_f32_e32 v66, v67, v66
	v_div_scale_f32 v67, vcc, v8, v13, v8
	v_mul_f32_e32 v68, v67, v66
	v_fma_f32 v69, -v65, v68, v67
	v_fmac_f32_e32 v68, v69, v66
	v_fma_f32 v65, -v65, v68, v67
	v_div_fmas_f32 v65, v65, v66, v68
	v_div_fixup_f32 v13, v65, v13, v8
	v_div_scale_f32 v8, s[6:7], v12, v12, v64
	v_rcp_f32_e32 v65, v8
	s_nop 0
	v_fma_f32 v66, -v8, v65, 1.0
	v_fmac_f32_e32 v65, v66, v65
	v_div_scale_f32 v66, vcc, v64, v12, v64
	v_mul_f32_e32 v67, v66, v65
	v_fma_f32 v68, -v8, v67, v66
	v_fmac_f32_e32 v67, v68, v65
	v_fma_f32 v8, -v8, v67, v66
	v_div_fmas_f32 v8, v8, v65, v67
	v_div_fixup_f32 v12, v8, v12, v64
	v_lshlrev_b32_e32 v64, 16, v9
	v_and_b32_e32 v65, 0xffff0000, v9
	v_mul_f32_e32 v8, 0xbfb8aa3b, v64
	v_mul_f32_e32 v9, 0xbfb8aa3b, v65
	v_exp_f32_e32 v8, v8
	v_exp_f32_e32 v9, v9
	v_pk_mul_f32 v[12:13], v[14:15], v[12:13]
	v_pk_mul_f32 v[14:15], v[74:75], v[0:1] op_sel_hi:[1,0]
	v_cvt_pk_bf16_f32 v12, v12, v13
	v_pk_add_f32 v[8:9], v[8:9], 1.0 op_sel_hi:[1,0]
	s_nop 0
	v_div_scale_f32 v66, s[6:7], v9, v9, v65
	v_rcp_f32_e32 v67, v66
	s_nop 0
	v_fma_f32 v68, -v66, v67, 1.0
	v_fmac_f32_e32 v67, v68, v67
	v_div_scale_f32 v68, vcc, v65, v9, v65
	v_mul_f32_e32 v69, v68, v67
	v_fma_f32 v70, -v66, v69, v68
	v_fmac_f32_e32 v69, v70, v67
	v_fma_f32 v66, -v66, v69, v68
	v_div_fmas_f32 v66, v66, v67, v69
	v_div_fixup_f32 v9, v66, v9, v65
	v_div_scale_f32 v65, s[6:7], v8, v8, v64
	v_rcp_f32_e32 v66, v65
	s_nop 0
	v_fma_f32 v67, -v65, v66, 1.0
	v_fmac_f32_e32 v66, v67, v66
	v_div_scale_f32 v67, vcc, v64, v8, v64
	v_mul_f32_e32 v68, v67, v66
	v_fma_f32 v69, -v65, v68, v67
	v_fmac_f32_e32 v68, v69, v66
	v_fma_f32 v65, -v65, v68, v67
	v_div_fmas_f32 v65, v65, v66, v68
	v_div_fixup_f32 v8, v65, v8, v64
	v_pk_mul_f32 v[8:9], v[14:15], v[8:9]
	v_pk_mul_f32 v[14:15], v[76:77], v[0:1] op_sel_hi:[1,0]
	v_cvt_pk_bf16_f32 v13, v8, v9
	global_load_dwordx2 v[8:9], v[6:7], off offset:48
	s_waitcnt vmcnt(0)
	v_lshlrev_b32_e32 v64, 16, v8
	v_and_b32_e32 v8, 0xffff0000, v8
	global_store_dwordx2 v[4:5], v[12:13], off offset:32
	v_mul_f32_e32 v12, 0xbfb8aa3b, v64
	v_mul_f32_e32 v13, 0xbfb8aa3b, v8
	v_exp_f32_e32 v12, v12
	v_exp_f32_e32 v13, v13
	s_nop 0
	v_pk_add_f32 v[12:13], v[12:13], 1.0 op_sel_hi:[1,0]
	s_nop 0
	v_div_scale_f32 v65, s[6:7], v13, v13, v8
	v_rcp_f32_e32 v66, v65
	s_nop 0
	v_fma_f32 v67, -v65, v66, 1.0
	v_fmac_f32_e32 v66, v67, v66
	v_div_scale_f32 v67, vcc, v8, v13, v8
	v_mul_f32_e32 v68, v67, v66
	v_fma_f32 v69, -v65, v68, v67
	v_fmac_f32_e32 v68, v69, v66
	v_fma_f32 v65, -v65, v68, v67
	v_div_fmas_f32 v65, v65, v66, v68
	v_div_fixup_f32 v13, v65, v13, v8
	v_div_scale_f32 v8, s[6:7], v12, v12, v64
	v_rcp_f32_e32 v65, v8
	s_nop 0
	v_fma_f32 v66, -v8, v65, 1.0
	v_fmac_f32_e32 v65, v66, v65
	v_div_scale_f32 v66, vcc, v64, v12, v64
	v_mul_f32_e32 v67, v66, v65
	v_fma_f32 v68, -v8, v67, v66
	v_fmac_f32_e32 v67, v68, v65
	v_fma_f32 v8, -v8, v67, v66
	v_div_fmas_f32 v8, v8, v65, v67
	v_div_fixup_f32 v12, v8, v12, v64
	v_lshlrev_b32_e32 v64, 16, v9
	v_and_b32_e32 v65, 0xffff0000, v9
	v_mul_f32_e32 v8, 0xbfb8aa3b, v64
	v_mul_f32_e32 v9, 0xbfb8aa3b, v65
	v_exp_f32_e32 v8, v8
	v_exp_f32_e32 v9, v9
	v_pk_mul_f32 v[12:13], v[14:15], v[12:13]
	v_pk_mul_f32 v[14:15], v[78:79], v[0:1] op_sel_hi:[1,0]
	v_cvt_pk_bf16_f32 v12, v12, v13
	v_pk_add_f32 v[8:9], v[8:9], 1.0 op_sel_hi:[1,0]
	s_nop 0
	v_div_scale_f32 v66, s[6:7], v9, v9, v65
	v_rcp_f32_e32 v67, v66
	s_nop 0
	v_fma_f32 v68, -v66, v67, 1.0
	v_fmac_f32_e32 v67, v68, v67
	v_div_scale_f32 v68, vcc, v65, v9, v65
	v_mul_f32_e32 v69, v68, v67
	v_fma_f32 v70, -v66, v69, v68
	v_fmac_f32_e32 v69, v70, v67
	v_fma_f32 v66, -v66, v69, v68
	v_div_fmas_f32 v66, v66, v67, v69
	v_div_fixup_f32 v9, v66, v9, v65
	v_div_scale_f32 v65, s[6:7], v8, v8, v64
	v_rcp_f32_e32 v66, v65
	s_nop 0
	v_fma_f32 v67, -v65, v66, 1.0
	v_fmac_f32_e32 v66, v67, v66
	v_div_scale_f32 v67, vcc, v64, v8, v64
	v_mul_f32_e32 v68, v67, v66
	v_fma_f32 v69, -v65, v68, v67
	v_fmac_f32_e32 v68, v69, v66
	v_fma_f32 v65, -v65, v68, v67
	v_div_fmas_f32 v65, v65, v66, v68
	v_div_fixup_f32 v8, v65, v8, v64
	v_pk_mul_f32 v[8:9], v[14:15], v[8:9]
	v_pk_mul_f32 v[14:15], v[48:49], v[0:1] op_sel_hi:[1,0]
	v_cvt_pk_bf16_f32 v13, v8, v9
	global_load_dwordx2 v[8:9], v[6:7], off offset:64
	s_waitcnt vmcnt(0)
	v_lshlrev_b32_e32 v64, 16, v8
	v_and_b32_e32 v8, 0xffff0000, v8
	global_store_dwordx2 v[4:5], v[12:13], off offset:48
	v_mul_f32_e32 v12, 0xbfb8aa3b, v64
	v_mul_f32_e32 v13, 0xbfb8aa3b, v8
	v_exp_f32_e32 v12, v12
	v_exp_f32_e32 v13, v13
	s_nop 0
	v_pk_add_f32 v[12:13], v[12:13], 1.0 op_sel_hi:[1,0]
	s_nop 0
	v_div_scale_f32 v48, s[6:7], v13, v13, v8
	v_rcp_f32_e32 v49, v48
	s_nop 0
	v_fma_f32 v65, -v48, v49, 1.0
	v_fmac_f32_e32 v49, v65, v49
	v_div_scale_f32 v65, vcc, v8, v13, v8
	v_mul_f32_e32 v66, v65, v49
	v_fma_f32 v67, -v48, v66, v65
	v_fmac_f32_e32 v66, v67, v49
	v_fma_f32 v48, -v48, v66, v65
	v_div_fmas_f32 v48, v48, v49, v66
	v_div_fixup_f32 v13, v48, v13, v8
	v_div_scale_f32 v8, s[6:7], v12, v12, v64
	v_rcp_f32_e32 v48, v8
	s_nop 0
	v_fma_f32 v49, -v8, v48, 1.0
	v_fmac_f32_e32 v48, v49, v48
	v_div_scale_f32 v49, vcc, v64, v12, v64
	v_mul_f32_e32 v65, v49, v48
	v_fma_f32 v66, -v8, v65, v49
	v_fmac_f32_e32 v65, v66, v48
	v_fma_f32 v8, -v8, v65, v49
	v_div_fmas_f32 v8, v8, v48, v65
	v_lshlrev_b32_e32 v48, 16, v9
	v_and_b32_e32 v49, 0xffff0000, v9
	v_div_fixup_f32 v12, v8, v12, v64
	v_mul_f32_e32 v8, 0xbfb8aa3b, v48
	v_mul_f32_e32 v9, 0xbfb8aa3b, v49
	v_exp_f32_e32 v8, v8
	v_exp_f32_e32 v9, v9
	v_pk_mul_f32 v[12:13], v[14:15], v[12:13]
	v_pk_mul_f32 v[14:15], v[50:51], v[0:1] op_sel_hi:[1,0]
	v_cvt_pk_bf16_f32 v12, v12, v13
	v_pk_add_f32 v[8:9], v[8:9], 1.0 op_sel_hi:[1,0]
	s_nop 0
	v_div_scale_f32 v50, s[6:7], v9, v9, v49
	v_rcp_f32_e32 v51, v50
	s_nop 0
	v_fma_f32 v64, -v50, v51, 1.0
	v_fmac_f32_e32 v51, v64, v51
	v_div_scale_f32 v64, vcc, v49, v9, v49
	v_mul_f32_e32 v65, v64, v51
	v_fma_f32 v66, -v50, v65, v64
	v_fmac_f32_e32 v65, v66, v51
	v_fma_f32 v50, -v50, v65, v64
	v_div_fmas_f32 v50, v50, v51, v65
	v_div_fixup_f32 v9, v50, v9, v49
	v_div_scale_f32 v49, s[6:7], v8, v8, v48
	v_rcp_f32_e32 v50, v49
	s_nop 0
	v_fma_f32 v51, -v49, v50, 1.0
	v_fmac_f32_e32 v50, v51, v50
	v_div_scale_f32 v51, vcc, v48, v8, v48
	v_mul_f32_e32 v64, v51, v50
	v_fma_f32 v65, -v49, v64, v51
	v_fmac_f32_e32 v64, v65, v50
	v_fma_f32 v49, -v49, v64, v51
	v_div_fmas_f32 v49, v49, v50, v64
	v_div_fixup_f32 v8, v49, v8, v48
	v_pk_mul_f32 v[8:9], v[14:15], v[8:9]
	v_pk_mul_f32 v[14:15], v[52:53], v[0:1] op_sel_hi:[1,0]
	v_cvt_pk_bf16_f32 v13, v8, v9
	global_load_dwordx2 v[8:9], v[6:7], off offset:80
	s_waitcnt vmcnt(0)
	v_lshlrev_b32_e32 v48, 16, v8
	v_and_b32_e32 v8, 0xffff0000, v8
	global_store_dwordx2 v[4:5], v[12:13], off offset:64
	v_mul_f32_e32 v12, 0xbfb8aa3b, v48
	v_mul_f32_e32 v13, 0xbfb8aa3b, v8
	v_exp_f32_e32 v12, v12
	v_exp_f32_e32 v13, v13
	s_nop 0
	v_pk_add_f32 v[12:13], v[12:13], 1.0 op_sel_hi:[1,0]
	s_nop 0
	v_div_scale_f32 v49, s[6:7], v13, v13, v8
	v_rcp_f32_e32 v50, v49
	s_nop 0
	v_fma_f32 v51, -v49, v50, 1.0
	v_fmac_f32_e32 v50, v51, v50
	v_div_scale_f32 v51, vcc, v8, v13, v8
	v_mul_f32_e32 v52, v51, v50
	v_fma_f32 v53, -v49, v52, v51
	v_fmac_f32_e32 v52, v53, v50
	v_fma_f32 v49, -v49, v52, v51
	v_div_fmas_f32 v49, v49, v50, v52
	v_div_fixup_f32 v13, v49, v13, v8
	v_div_scale_f32 v8, s[6:7], v12, v12, v48
	v_rcp_f32_e32 v49, v8
	s_nop 0
	v_fma_f32 v50, -v8, v49, 1.0
	v_fmac_f32_e32 v49, v50, v49
	v_div_scale_f32 v50, vcc, v48, v12, v48
	v_mul_f32_e32 v51, v50, v49
	v_fma_f32 v52, -v8, v51, v50
	v_fmac_f32_e32 v51, v52, v49
	v_fma_f32 v8, -v8, v51, v50
	v_div_fmas_f32 v8, v8, v49, v51
	v_div_fixup_f32 v12, v8, v12, v48
	v_lshlrev_b32_e32 v48, 16, v9
	v_and_b32_e32 v49, 0xffff0000, v9
	v_mul_f32_e32 v8, 0xbfb8aa3b, v48
	v_mul_f32_e32 v9, 0xbfb8aa3b, v49
	v_exp_f32_e32 v8, v8
	v_exp_f32_e32 v9, v9
	v_pk_mul_f32 v[12:13], v[14:15], v[12:13]
	v_pk_mul_f32 v[14:15], v[54:55], v[0:1] op_sel_hi:[1,0]
	v_cvt_pk_bf16_f32 v12, v12, v13
	v_pk_add_f32 v[8:9], v[8:9], 1.0 op_sel_hi:[1,0]
	s_nop 0
	v_div_scale_f32 v50, s[6:7], v9, v9, v49
	v_rcp_f32_e32 v51, v50
	s_nop 0
	v_fma_f32 v52, -v50, v51, 1.0
	v_fmac_f32_e32 v51, v52, v51
	v_div_scale_f32 v52, vcc, v49, v9, v49
	v_mul_f32_e32 v53, v52, v51
	v_fma_f32 v54, -v50, v53, v52
	v_fmac_f32_e32 v53, v54, v51
	v_fma_f32 v50, -v50, v53, v52
	v_div_fmas_f32 v50, v50, v51, v53
	v_div_fixup_f32 v9, v50, v9, v49
	v_div_scale_f32 v49, s[6:7], v8, v8, v48
	v_rcp_f32_e32 v50, v49
	s_nop 0
	v_fma_f32 v51, -v49, v50, 1.0
	v_fmac_f32_e32 v50, v51, v50
	v_div_scale_f32 v51, vcc, v48, v8, v48
	v_mul_f32_e32 v52, v51, v50
	v_fma_f32 v53, -v49, v52, v51
	v_fmac_f32_e32 v52, v53, v50
	v_fma_f32 v49, -v49, v52, v51
	v_div_fmas_f32 v49, v49, v50, v52
	v_div_fixup_f32 v8, v49, v8, v48
	v_pk_mul_f32 v[8:9], v[14:15], v[8:9]
	v_pk_mul_f32 v[14:15], v[56:57], v[0:1] op_sel_hi:[1,0]
	v_cvt_pk_bf16_f32 v13, v8, v9
	global_load_dwordx2 v[8:9], v[6:7], off offset:96
	s_waitcnt vmcnt(0)
	v_lshlrev_b32_e32 v48, 16, v8
	global_load_dwordx2 v[6:7], v[6:7], off offset:112
	v_and_b32_e32 v8, 0xffff0000, v8
	global_store_dwordx2 v[4:5], v[12:13], off offset:80
	v_mul_f32_e32 v12, 0xbfb8aa3b, v48
	v_mul_f32_e32 v13, 0xbfb8aa3b, v8
	v_exp_f32_e32 v12, v12
	v_exp_f32_e32 v13, v13
	s_nop 0
	v_pk_add_f32 v[12:13], v[12:13], 1.0 op_sel_hi:[1,0]
	s_nop 0
	v_div_scale_f32 v49, s[6:7], v13, v13, v8
	v_rcp_f32_e32 v50, v49
	s_nop 0
	v_fma_f32 v51, -v49, v50, 1.0
	v_fmac_f32_e32 v50, v51, v50
	v_div_scale_f32 v51, vcc, v8, v13, v8
	v_mul_f32_e32 v52, v51, v50
	v_fma_f32 v53, -v49, v52, v51
	v_fmac_f32_e32 v52, v53, v50
	v_fma_f32 v49, -v49, v52, v51
	v_div_fmas_f32 v49, v49, v50, v52
	v_div_fixup_f32 v13, v49, v13, v8
	v_div_scale_f32 v8, s[6:7], v12, v12, v48
	v_rcp_f32_e32 v49, v8
	s_nop 0
	v_fma_f32 v50, -v8, v49, 1.0
	v_fmac_f32_e32 v49, v50, v49
	v_div_scale_f32 v50, vcc, v48, v12, v48
	v_mul_f32_e32 v51, v50, v49
	v_fma_f32 v52, -v8, v51, v50
	v_fmac_f32_e32 v51, v52, v49
	v_fma_f32 v8, -v8, v51, v50
	v_div_fmas_f32 v8, v8, v49, v51
	v_div_fixup_f32 v12, v8, v12, v48
	v_lshlrev_b32_e32 v48, 16, v9
	v_and_b32_e32 v49, 0xffff0000, v9
	v_mul_f32_e32 v8, 0xbfb8aa3b, v48
	v_mul_f32_e32 v9, 0xbfb8aa3b, v49
	v_exp_f32_e32 v8, v8
	v_exp_f32_e32 v9, v9
	v_pk_mul_f32 v[12:13], v[14:15], v[12:13]
	v_pk_mul_f32 v[14:15], v[58:59], v[0:1] op_sel_hi:[1,0]
	v_cvt_pk_bf16_f32 v12, v12, v13
	v_pk_add_f32 v[8:9], v[8:9], 1.0 op_sel_hi:[1,0]
	s_nop 0
	v_div_scale_f32 v50, s[6:7], v9, v9, v49
	v_rcp_f32_e32 v51, v50
	s_nop 0
	v_fma_f32 v52, -v50, v51, 1.0
	v_fmac_f32_e32 v51, v52, v51
	v_div_scale_f32 v52, vcc, v49, v9, v49
	v_mul_f32_e32 v53, v52, v51
	v_fma_f32 v54, -v50, v53, v52
	v_fmac_f32_e32 v53, v54, v51
	v_fma_f32 v50, -v50, v53, v52
	v_div_fmas_f32 v50, v50, v51, v53
	v_div_fixup_f32 v9, v50, v9, v49
	v_div_scale_f32 v49, s[6:7], v8, v8, v48
	v_rcp_f32_e32 v50, v49
	s_nop 0
	v_fma_f32 v51, -v49, v50, 1.0
	v_fmac_f32_e32 v50, v51, v50
	v_div_scale_f32 v51, vcc, v48, v8, v48
	v_mul_f32_e32 v52, v51, v50
	v_fma_f32 v53, -v49, v52, v51
	v_fmac_f32_e32 v52, v53, v50
	v_fma_f32 v49, -v49, v52, v51
	v_div_fmas_f32 v49, v49, v50, v52
	v_div_fixup_f32 v8, v49, v8, v48
	v_pk_mul_f32 v[8:9], v[14:15], v[8:9]
	s_waitcnt vmcnt(1)
	v_lshlrev_b32_e32 v14, 16, v6
	v_and_b32_e32 v6, 0xffff0000, v6
	v_cvt_pk_bf16_f32 v13, v8, v9
	v_mul_f32_e32 v8, 0xbfb8aa3b, v14
	v_mul_f32_e32 v9, 0xbfb8aa3b, v6
	v_exp_f32_e32 v8, v8
	v_exp_f32_e32 v9, v9
	global_store_dwordx2 v[4:5], v[12:13], off offset:96
	v_pk_mul_f32 v[12:13], v[60:61], v[0:1] op_sel_hi:[1,0]
	v_pk_add_f32 v[8:9], v[8:9], 1.0 op_sel_hi:[1,0]
	s_nop 0
	v_div_scale_f32 v15, s[6:7], v9, v9, v6
	v_rcp_f32_e32 v48, v15
	s_nop 0
	v_fma_f32 v49, -v15, v48, 1.0
	v_fmac_f32_e32 v48, v49, v48
	v_div_scale_f32 v49, vcc, v6, v9, v6
	v_mul_f32_e32 v50, v49, v48
	v_fma_f32 v51, -v15, v50, v49
	v_fmac_f32_e32 v50, v51, v48
	v_fma_f32 v15, -v15, v50, v49
	v_div_fmas_f32 v15, v15, v48, v50
	v_div_fixup_f32 v9, v15, v9, v6
	v_div_scale_f32 v6, s[6:7], v8, v8, v14
	v_rcp_f32_e32 v15, v6
	s_nop 0
	v_fma_f32 v48, -v6, v15, 1.0
	v_fmac_f32_e32 v15, v48, v15
	v_div_scale_f32 v48, vcc, v14, v8, v14
	v_mul_f32_e32 v49, v48, v15
	v_fma_f32 v50, -v6, v49, v48
	v_fmac_f32_e32 v49, v50, v15
	v_fma_f32 v6, -v6, v49, v48
	v_div_fmas_f32 v6, v6, v15, v49
	v_div_fixup_f32 v8, v6, v8, v14
	v_lshlrev_b32_e32 v14, 16, v7
	v_and_b32_e32 v15, 0xffff0000, v7
	v_pk_mul_f32 v[8:9], v[12:13], v[8:9]
	v_mul_f32_e32 v6, 0xbfb8aa3b, v14
	v_pk_mul_f32 v[12:13], v[62:63], v[0:1] op_sel_hi:[1,0]
	v_mul_f32_e32 v0, 0xbfb8aa3b, v15
	v_exp_f32_e32 v6, v6
	v_exp_f32_e32 v7, v0
	v_cvt_pk_bf16_f32 v8, v8, v9
	v_pk_add_f32 v[6:7], v[6:7], 1.0 op_sel_hi:[1,0]
	s_nop 0
	v_div_scale_f32 v0, s[6:7], v7, v7, v15
	v_rcp_f32_e32 v48, v0
	s_nop 0
	v_fma_f32 v49, -v0, v48, 1.0
	v_fmac_f32_e32 v48, v49, v48
	v_div_scale_f32 v49, vcc, v15, v7, v15
	v_mul_f32_e32 v50, v49, v48
	v_fma_f32 v51, -v0, v50, v49
	v_fmac_f32_e32 v50, v51, v48
	v_fma_f32 v0, -v0, v50, v49
	v_div_fmas_f32 v0, v0, v48, v50
	v_div_fixup_f32 v7, v0, v7, v15
	v_div_scale_f32 v0, s[6:7], v6, v6, v14
	v_rcp_f32_e32 v15, v0
	s_movk_i32 s6, 0x7e0
	v_fma_f32 v48, -v0, v15, 1.0
	v_fmac_f32_e32 v15, v48, v15
	v_div_scale_f32 v48, vcc, v14, v6, v14
	v_mul_f32_e32 v49, v48, v15
	v_fma_f32 v50, -v0, v49, v48
	v_fmac_f32_e32 v49, v50, v15
	v_fma_f32 v0, -v0, v49, v48
	v_div_fmas_f32 v0, v0, v15, v49
	v_div_fixup_f32 v6, v0, v6, v14
	v_pk_mul_f32 v[6:7], v[12:13], v[6:7]
	v_cmp_gt_i32_e32 vcc, s6, v188
	v_cvt_pk_bf16_f32 v9, v6, v7
	global_store_dwordx2 v[4:5], v[8:9], off offset:112
	v_cndmask_b32_e32 v0, v10, v11, vcc
	v_add3_u32 v4, v0, v188, 32
	ds_bpermute_b32 v0, v189, v195
	v_ashrrev_i32_e32 v5, 31, v4
	v_mad_i64_i32 v[2:3], s[6:7], v4, s3, v[2:3]
	v_lshlrev_b64 v[4:5], 11, v[4:5]
	s_waitcnt lgkmcnt(0)
	v_add_f32_e32 v0, v195, v0
	v_lshl_add_u64 v[6:7], s[0:1], 0, v[4:5]
	v_div_scale_f32 v4, s[0:1], v0, v0, 1.0
	v_rcp_f32_e32 v5, v4
	s_nop 0
	v_fma_f32 v8, -v4, v5, 1.0
	v_fmac_f32_e32 v5, v8, v5
	v_div_scale_f32 v8, vcc, 1.0, v0, 1.0
	v_mul_f32_e32 v9, v8, v5
	v_fma_f32 v10, -v4, v9, v8
	v_fmac_f32_e32 v9, v10, v5
	v_fma_f32 v4, -v4, v9, v8
	v_div_fmas_f32 v4, v4, v5, v9
	v_div_fixup_f32 v0, v4, v0, 1.0
	v_lshl_add_u64 v[4:5], v[2:3], 0, v[190:191]
	global_load_dwordx2 v[2:3], v[4:5], off
	v_pk_mul_f32 v[10:11], v[32:33], v[0:1] op_sel_hi:[1,0]
	s_waitcnt vmcnt(0)
	v_lshlrev_b32_e32 v12, 16, v2
	v_and_b32_e32 v2, 0xffff0000, v2
	v_mul_f32_e32 v8, 0xbfb8aa3b, v12
	v_mul_f32_e32 v9, 0xbfb8aa3b, v2
	v_exp_f32_e32 v8, v8
	v_exp_f32_e32 v9, v9
	s_nop 0
	v_pk_add_f32 v[8:9], v[8:9], 1.0 op_sel_hi:[1,0]
	s_nop 0
	v_div_scale_f32 v13, s[0:1], v9, v9, v2
	v_rcp_f32_e32 v14, v13
	s_nop 0
	v_fma_f32 v15, -v13, v14, 1.0
	v_fmac_f32_e32 v14, v15, v14
	v_div_scale_f32 v15, vcc, v2, v9, v2
	v_mul_f32_e32 v32, v15, v14
	v_fma_f32 v33, -v13, v32, v15
	v_fmac_f32_e32 v32, v33, v14
	v_fma_f32 v13, -v13, v32, v15
	v_div_fmas_f32 v13, v13, v14, v32
	v_div_fixup_f32 v9, v13, v9, v2
	v_div_scale_f32 v2, s[0:1], v8, v8, v12
	v_rcp_f32_e32 v13, v2
	s_nop 0
	v_fma_f32 v14, -v2, v13, 1.0
	v_fmac_f32_e32 v13, v14, v13
	v_div_scale_f32 v14, vcc, v12, v8, v12
	v_mul_f32_e32 v15, v14, v13
	v_fma_f32 v32, -v2, v15, v14
	v_fmac_f32_e32 v15, v32, v13
	v_fma_f32 v2, -v2, v15, v14
	v_div_fmas_f32 v2, v2, v13, v15
	v_div_fixup_f32 v8, v2, v8, v12
	v_lshlrev_b32_e32 v12, 16, v3
	v_and_b32_e32 v13, 0xffff0000, v3
	v_mul_f32_e32 v2, 0xbfb8aa3b, v12
	v_mul_f32_e32 v3, 0xbfb8aa3b, v13
	v_exp_f32_e32 v2, v2
	v_exp_f32_e32 v3, v3
	v_pk_mul_f32 v[8:9], v[10:11], v[8:9]
	v_pk_mul_f32 v[10:11], v[34:35], v[0:1] op_sel_hi:[1,0]
	v_cvt_pk_bf16_f32 v8, v8, v9
	v_pk_add_f32 v[2:3], v[2:3], 1.0 op_sel_hi:[1,0]
	s_nop 0
	v_div_scale_f32 v14, s[0:1], v3, v3, v13
	v_rcp_f32_e32 v15, v14
	s_nop 0
	v_fma_f32 v32, -v14, v15, 1.0
	v_fmac_f32_e32 v15, v32, v15
	v_div_scale_f32 v32, vcc, v13, v3, v13
	v_mul_f32_e32 v33, v32, v15
	v_fma_f32 v34, -v14, v33, v32
	v_fmac_f32_e32 v33, v34, v15
	v_fma_f32 v14, -v14, v33, v32
	v_div_fmas_f32 v14, v14, v15, v33
	v_div_fixup_f32 v3, v14, v3, v13
	v_div_scale_f32 v13, s[0:1], v2, v2, v12
	v_rcp_f32_e32 v14, v13
	s_nop 0
	v_fma_f32 v15, -v13, v14, 1.0
	v_fmac_f32_e32 v14, v15, v14
	v_div_scale_f32 v15, vcc, v12, v2, v12
	v_mul_f32_e32 v32, v15, v14
	v_fma_f32 v33, -v13, v32, v15
	v_fmac_f32_e32 v32, v33, v14
	v_fma_f32 v13, -v13, v32, v15
	v_div_fmas_f32 v13, v13, v14, v32
	v_div_fixup_f32 v2, v13, v2, v12
	v_pk_mul_f32 v[2:3], v[10:11], v[2:3]
	v_pk_mul_f32 v[10:11], v[36:37], v[0:1] op_sel_hi:[1,0]
	v_cvt_pk_bf16_f32 v9, v2, v3
	v_lshl_add_u64 v[2:3], v[6:7], 0, v[190:191]
	global_load_dwordx2 v[6:7], v[4:5], off offset:16
	s_waitcnt vmcnt(0)
	v_lshlrev_b32_e32 v12, 16, v6
	v_and_b32_e32 v6, 0xffff0000, v6
	global_store_dwordx2 v[2:3], v[8:9], off
	v_mul_f32_e32 v8, 0xbfb8aa3b, v12
	v_mul_f32_e32 v9, 0xbfb8aa3b, v6
	v_exp_f32_e32 v8, v8
	v_exp_f32_e32 v9, v9
	s_nop 0
	v_pk_add_f32 v[8:9], v[8:9], 1.0 op_sel_hi:[1,0]
	s_nop 0
	v_div_scale_f32 v13, s[0:1], v9, v9, v6
	v_rcp_f32_e32 v14, v13
	s_nop 0
	v_fma_f32 v15, -v13, v14, 1.0
	v_fmac_f32_e32 v14, v15, v14
	v_div_scale_f32 v15, vcc, v6, v9, v6
	v_mul_f32_e32 v32, v15, v14
	v_fma_f32 v33, -v13, v32, v15
	v_fmac_f32_e32 v32, v33, v14
	v_fma_f32 v13, -v13, v32, v15
	v_div_fmas_f32 v13, v13, v14, v32
	v_div_fixup_f32 v9, v13, v9, v6
	v_div_scale_f32 v6, s[0:1], v8, v8, v12
	v_rcp_f32_e32 v13, v6
	s_nop 0
	v_fma_f32 v14, -v6, v13, 1.0
	v_fmac_f32_e32 v13, v14, v13
	v_div_scale_f32 v14, vcc, v12, v8, v12
	v_mul_f32_e32 v15, v14, v13
	v_fma_f32 v32, -v6, v15, v14
	v_fmac_f32_e32 v15, v32, v13
	v_fma_f32 v6, -v6, v15, v14
	v_div_fmas_f32 v6, v6, v13, v15
	v_div_fixup_f32 v8, v6, v8, v12
	v_lshlrev_b32_e32 v12, 16, v7
	v_and_b32_e32 v13, 0xffff0000, v7
	v_mul_f32_e32 v6, 0xbfb8aa3b, v12
	v_mul_f32_e32 v7, 0xbfb8aa3b, v13
	v_exp_f32_e32 v6, v6
	v_exp_f32_e32 v7, v7
	v_pk_mul_f32 v[8:9], v[10:11], v[8:9]
	v_pk_mul_f32 v[10:11], v[38:39], v[0:1] op_sel_hi:[1,0]
	v_cvt_pk_bf16_f32 v8, v8, v9
	v_pk_add_f32 v[6:7], v[6:7], 1.0 op_sel_hi:[1,0]
	s_nop 0
	v_div_scale_f32 v14, s[0:1], v7, v7, v13
	v_rcp_f32_e32 v15, v14
	s_nop 0
	v_fma_f32 v32, -v14, v15, 1.0
	v_fmac_f32_e32 v15, v32, v15
	v_div_scale_f32 v32, vcc, v13, v7, v13
	v_mul_f32_e32 v33, v32, v15
	v_fma_f32 v34, -v14, v33, v32
	v_fmac_f32_e32 v33, v34, v15
	v_fma_f32 v14, -v14, v33, v32
	v_div_fmas_f32 v14, v14, v15, v33
	v_div_fixup_f32 v7, v14, v7, v13
	v_div_scale_f32 v13, s[0:1], v6, v6, v12
	v_rcp_f32_e32 v14, v13
	s_nop 0
	v_fma_f32 v15, -v13, v14, 1.0
	v_fmac_f32_e32 v14, v15, v14
	v_div_scale_f32 v15, vcc, v12, v6, v12
	v_mul_f32_e32 v32, v15, v14
	v_fma_f32 v33, -v13, v32, v15
	v_fmac_f32_e32 v32, v33, v14
	v_fma_f32 v13, -v13, v32, v15
	v_div_fmas_f32 v13, v13, v14, v32
	v_div_fixup_f32 v6, v13, v6, v12
	v_pk_mul_f32 v[6:7], v[10:11], v[6:7]
	v_pk_mul_f32 v[10:11], v[40:41], v[0:1] op_sel_hi:[1,0]
	v_cvt_pk_bf16_f32 v9, v6, v7
	global_load_dwordx2 v[6:7], v[4:5], off offset:32
	s_waitcnt vmcnt(0)
	v_lshlrev_b32_e32 v12, 16, v6
	v_and_b32_e32 v6, 0xffff0000, v6
	global_store_dwordx2 v[2:3], v[8:9], off offset:16
	v_mul_f32_e32 v8, 0xbfb8aa3b, v12
	v_mul_f32_e32 v9, 0xbfb8aa3b, v6
	v_exp_f32_e32 v8, v8
	v_exp_f32_e32 v9, v9
	s_nop 0
	v_pk_add_f32 v[8:9], v[8:9], 1.0 op_sel_hi:[1,0]
	s_nop 0
	v_div_scale_f32 v13, s[0:1], v9, v9, v6
	v_rcp_f32_e32 v14, v13
	s_nop 0
	v_fma_f32 v15, -v13, v14, 1.0
	v_fmac_f32_e32 v14, v15, v14
	v_div_scale_f32 v15, vcc, v6, v9, v6
	v_mul_f32_e32 v32, v15, v14
	v_fma_f32 v33, -v13, v32, v15
	v_fmac_f32_e32 v32, v33, v14
	v_fma_f32 v13, -v13, v32, v15
	v_div_fmas_f32 v13, v13, v14, v32
	v_div_fixup_f32 v9, v13, v9, v6
	v_div_scale_f32 v6, s[0:1], v8, v8, v12
	v_rcp_f32_e32 v13, v6
	s_nop 0
	v_fma_f32 v14, -v6, v13, 1.0
	v_fmac_f32_e32 v13, v14, v13
	v_div_scale_f32 v14, vcc, v12, v8, v12
	v_mul_f32_e32 v15, v14, v13
	v_fma_f32 v32, -v6, v15, v14
	v_fmac_f32_e32 v15, v32, v13
	v_fma_f32 v6, -v6, v15, v14
	v_div_fmas_f32 v6, v6, v13, v15
	v_div_fixup_f32 v8, v6, v8, v12
	v_lshlrev_b32_e32 v12, 16, v7
	v_and_b32_e32 v13, 0xffff0000, v7
	v_mul_f32_e32 v6, 0xbfb8aa3b, v12
	v_mul_f32_e32 v7, 0xbfb8aa3b, v13
	v_exp_f32_e32 v6, v6
	v_exp_f32_e32 v7, v7
	v_pk_mul_f32 v[8:9], v[10:11], v[8:9]
	v_pk_mul_f32 v[10:11], v[42:43], v[0:1] op_sel_hi:[1,0]
	v_cvt_pk_bf16_f32 v8, v8, v9
	v_pk_add_f32 v[6:7], v[6:7], 1.0 op_sel_hi:[1,0]
	s_nop 0
	v_div_scale_f32 v14, s[0:1], v7, v7, v13
	v_rcp_f32_e32 v15, v14
	s_nop 0
	v_fma_f32 v32, -v14, v15, 1.0
	v_fmac_f32_e32 v15, v32, v15
	v_div_scale_f32 v32, vcc, v13, v7, v13
	v_mul_f32_e32 v33, v32, v15
	v_fma_f32 v34, -v14, v33, v32
	v_fmac_f32_e32 v33, v34, v15
	v_fma_f32 v14, -v14, v33, v32
	v_div_fmas_f32 v14, v14, v15, v33
	v_div_fixup_f32 v7, v14, v7, v13
	v_div_scale_f32 v13, s[0:1], v6, v6, v12
	v_rcp_f32_e32 v14, v13
	s_nop 0
	v_fma_f32 v15, -v13, v14, 1.0
	v_fmac_f32_e32 v14, v15, v14
	v_div_scale_f32 v15, vcc, v12, v6, v12
	v_mul_f32_e32 v32, v15, v14
	v_fma_f32 v33, -v13, v32, v15
	v_fmac_f32_e32 v32, v33, v14
	v_fma_f32 v13, -v13, v32, v15
	v_div_fmas_f32 v13, v13, v14, v32
	v_div_fixup_f32 v6, v13, v6, v12
	v_pk_mul_f32 v[6:7], v[10:11], v[6:7]
	v_pk_mul_f32 v[10:11], v[44:45], v[0:1] op_sel_hi:[1,0]
	v_cvt_pk_bf16_f32 v9, v6, v7
	global_load_dwordx2 v[6:7], v[4:5], off offset:48
	s_waitcnt vmcnt(0)
	v_lshlrev_b32_e32 v12, 16, v6
	v_and_b32_e32 v6, 0xffff0000, v6
	global_store_dwordx2 v[2:3], v[8:9], off offset:32
	v_mul_f32_e32 v8, 0xbfb8aa3b, v12
	v_mul_f32_e32 v9, 0xbfb8aa3b, v6
	v_exp_f32_e32 v8, v8
	v_exp_f32_e32 v9, v9
	s_nop 0
	v_pk_add_f32 v[8:9], v[8:9], 1.0 op_sel_hi:[1,0]
	s_nop 0
	v_div_scale_f32 v13, s[0:1], v9, v9, v6
	v_rcp_f32_e32 v14, v13
	s_nop 0
	v_fma_f32 v15, -v13, v14, 1.0
	v_fmac_f32_e32 v14, v15, v14
	v_div_scale_f32 v15, vcc, v6, v9, v6
	v_mul_f32_e32 v32, v15, v14
	v_fma_f32 v33, -v13, v32, v15
	v_fmac_f32_e32 v32, v33, v14
	v_fma_f32 v13, -v13, v32, v15
	v_div_fmas_f32 v13, v13, v14, v32
	v_div_fixup_f32 v9, v13, v9, v6
	v_div_scale_f32 v6, s[0:1], v8, v8, v12
	v_rcp_f32_e32 v13, v6
	s_nop 0
	v_fma_f32 v14, -v6, v13, 1.0
	v_fmac_f32_e32 v13, v14, v13
	v_div_scale_f32 v14, vcc, v12, v8, v12
	v_mul_f32_e32 v15, v14, v13
	v_fma_f32 v32, -v6, v15, v14
	v_fmac_f32_e32 v15, v32, v13
	v_fma_f32 v6, -v6, v15, v14
	v_div_fmas_f32 v6, v6, v13, v15
	v_div_fixup_f32 v8, v6, v8, v12
	v_lshlrev_b32_e32 v12, 16, v7
	v_and_b32_e32 v13, 0xffff0000, v7
	v_mul_f32_e32 v6, 0xbfb8aa3b, v12
	v_mul_f32_e32 v7, 0xbfb8aa3b, v13
	v_exp_f32_e32 v6, v6
	v_exp_f32_e32 v7, v7
	v_pk_mul_f32 v[8:9], v[10:11], v[8:9]
	v_pk_mul_f32 v[10:11], v[46:47], v[0:1] op_sel_hi:[1,0]
	v_cvt_pk_bf16_f32 v8, v8, v9
	v_pk_add_f32 v[6:7], v[6:7], 1.0 op_sel_hi:[1,0]
	s_nop 0
	v_div_scale_f32 v14, s[0:1], v7, v7, v13
	v_rcp_f32_e32 v15, v14
	s_nop 0
	v_fma_f32 v32, -v14, v15, 1.0
	v_fmac_f32_e32 v15, v32, v15
	v_div_scale_f32 v32, vcc, v13, v7, v13
	v_mul_f32_e32 v33, v32, v15
	v_fma_f32 v34, -v14, v33, v32
	v_fmac_f32_e32 v33, v34, v15
	v_fma_f32 v14, -v14, v33, v32
	v_div_fmas_f32 v14, v14, v15, v33
	v_div_fixup_f32 v7, v14, v7, v13
	v_div_scale_f32 v13, s[0:1], v6, v6, v12
	v_rcp_f32_e32 v14, v13
	s_nop 0
	v_fma_f32 v15, -v13, v14, 1.0
	v_fmac_f32_e32 v14, v15, v14
	v_div_scale_f32 v15, vcc, v12, v6, v12
	v_mul_f32_e32 v32, v15, v14
	v_fma_f32 v33, -v13, v32, v15
	v_fmac_f32_e32 v32, v33, v14
	v_fma_f32 v13, -v13, v32, v15
	v_div_fmas_f32 v13, v13, v14, v32
	v_div_fixup_f32 v6, v13, v6, v12
	v_pk_mul_f32 v[6:7], v[10:11], v[6:7]
	v_pk_mul_f32 v[10:11], v[16:17], v[0:1] op_sel_hi:[1,0]
	v_cvt_pk_bf16_f32 v9, v6, v7
	global_load_dwordx2 v[6:7], v[4:5], off offset:64
	s_waitcnt vmcnt(0)
	v_lshlrev_b32_e32 v12, 16, v6
	v_and_b32_e32 v6, 0xffff0000, v6
	global_store_dwordx2 v[2:3], v[8:9], off offset:48
	v_mul_f32_e32 v8, 0xbfb8aa3b, v12
	v_mul_f32_e32 v9, 0xbfb8aa3b, v6
	v_exp_f32_e32 v8, v8
	v_exp_f32_e32 v9, v9
	s_nop 0
	v_pk_add_f32 v[8:9], v[8:9], 1.0 op_sel_hi:[1,0]
	s_nop 0
	v_div_scale_f32 v13, s[0:1], v9, v9, v6
	v_rcp_f32_e32 v14, v13
	s_nop 0
	v_fma_f32 v15, -v13, v14, 1.0
	v_fmac_f32_e32 v14, v15, v14
	v_div_scale_f32 v15, vcc, v6, v9, v6
	v_mul_f32_e32 v16, v15, v14
	v_fma_f32 v17, -v13, v16, v15
	v_fmac_f32_e32 v16, v17, v14
	v_fma_f32 v13, -v13, v16, v15
	v_div_fmas_f32 v13, v13, v14, v16
	v_div_fixup_f32 v9, v13, v9, v6
	v_div_scale_f32 v6, s[0:1], v8, v8, v12
	v_rcp_f32_e32 v13, v6
	s_nop 0
	v_fma_f32 v14, -v6, v13, 1.0
	v_fmac_f32_e32 v13, v14, v13
	v_div_scale_f32 v14, vcc, v12, v8, v12
	v_mul_f32_e32 v15, v14, v13
	v_fma_f32 v16, -v6, v15, v14
	v_fmac_f32_e32 v15, v16, v13
	v_fma_f32 v6, -v6, v15, v14
	v_div_fmas_f32 v6, v6, v13, v15
	v_div_fixup_f32 v8, v6, v8, v12
	v_lshlrev_b32_e32 v12, 16, v7
	v_and_b32_e32 v13, 0xffff0000, v7
	v_mul_f32_e32 v6, 0xbfb8aa3b, v12
	v_mul_f32_e32 v7, 0xbfb8aa3b, v13
	v_exp_f32_e32 v6, v6
	v_exp_f32_e32 v7, v7
	v_pk_mul_f32 v[8:9], v[10:11], v[8:9]
	v_pk_mul_f32 v[10:11], v[18:19], v[0:1] op_sel_hi:[1,0]
	v_cvt_pk_bf16_f32 v8, v8, v9
	v_pk_add_f32 v[6:7], v[6:7], 1.0 op_sel_hi:[1,0]
	s_nop 0
	v_div_scale_f32 v14, s[0:1], v7, v7, v13
	v_rcp_f32_e32 v15, v14
	s_nop 0
	v_fma_f32 v16, -v14, v15, 1.0
	v_fmac_f32_e32 v15, v16, v15
	v_div_scale_f32 v16, vcc, v13, v7, v13
	v_mul_f32_e32 v17, v16, v15
	v_fma_f32 v18, -v14, v17, v16
	v_fmac_f32_e32 v17, v18, v15
	v_fma_f32 v14, -v14, v17, v16
	v_div_fmas_f32 v14, v14, v15, v17
	v_div_fixup_f32 v7, v14, v7, v13
	v_div_scale_f32 v13, s[0:1], v6, v6, v12
	v_rcp_f32_e32 v14, v13
	s_nop 0
	v_fma_f32 v15, -v13, v14, 1.0
	v_fmac_f32_e32 v14, v15, v14
	v_div_scale_f32 v15, vcc, v12, v6, v12
	v_mul_f32_e32 v16, v15, v14
	v_fma_f32 v17, -v13, v16, v15
	v_fmac_f32_e32 v16, v17, v14
	v_fma_f32 v13, -v13, v16, v15
	v_div_fmas_f32 v13, v13, v14, v16
	v_div_fixup_f32 v6, v13, v6, v12
	v_pk_mul_f32 v[6:7], v[10:11], v[6:7]
	v_pk_mul_f32 v[10:11], v[20:21], v[0:1] op_sel_hi:[1,0]
	v_cvt_pk_bf16_f32 v9, v6, v7
	global_load_dwordx2 v[6:7], v[4:5], off offset:80
	s_waitcnt vmcnt(0)
	v_lshlrev_b32_e32 v12, 16, v6
	v_and_b32_e32 v6, 0xffff0000, v6
	global_store_dwordx2 v[2:3], v[8:9], off offset:64
	v_mul_f32_e32 v8, 0xbfb8aa3b, v12
	v_mul_f32_e32 v9, 0xbfb8aa3b, v6
	v_exp_f32_e32 v8, v8
	v_exp_f32_e32 v9, v9
	s_nop 0
	v_pk_add_f32 v[8:9], v[8:9], 1.0 op_sel_hi:[1,0]
	s_nop 0
	v_div_scale_f32 v13, s[0:1], v9, v9, v6
	v_rcp_f32_e32 v14, v13
	s_nop 0
	v_fma_f32 v15, -v13, v14, 1.0
	v_fmac_f32_e32 v14, v15, v14
	v_div_scale_f32 v15, vcc, v6, v9, v6
	v_mul_f32_e32 v16, v15, v14
	v_fma_f32 v17, -v13, v16, v15
	v_fmac_f32_e32 v16, v17, v14
	v_fma_f32 v13, -v13, v16, v15
	v_div_fmas_f32 v13, v13, v14, v16
	v_div_fixup_f32 v9, v13, v9, v6
	v_div_scale_f32 v6, s[0:1], v8, v8, v12
	v_rcp_f32_e32 v13, v6
	s_nop 0
	v_fma_f32 v14, -v6, v13, 1.0
	v_fmac_f32_e32 v13, v14, v13
	v_div_scale_f32 v14, vcc, v12, v8, v12
	v_mul_f32_e32 v15, v14, v13
	v_fma_f32 v16, -v6, v15, v14
	v_fmac_f32_e32 v15, v16, v13
	v_fma_f32 v6, -v6, v15, v14
	v_div_fmas_f32 v6, v6, v13, v15
	v_div_fixup_f32 v8, v6, v8, v12
	v_lshlrev_b32_e32 v12, 16, v7
	v_and_b32_e32 v13, 0xffff0000, v7
	v_mul_f32_e32 v6, 0xbfb8aa3b, v12
	v_mul_f32_e32 v7, 0xbfb8aa3b, v13
	v_exp_f32_e32 v6, v6
	v_exp_f32_e32 v7, v7
	v_pk_mul_f32 v[8:9], v[10:11], v[8:9]
	v_pk_mul_f32 v[10:11], v[22:23], v[0:1] op_sel_hi:[1,0]
	v_cvt_pk_bf16_f32 v8, v8, v9
	v_pk_add_f32 v[6:7], v[6:7], 1.0 op_sel_hi:[1,0]
	s_nop 0
	v_div_scale_f32 v14, s[0:1], v7, v7, v13
	v_rcp_f32_e32 v15, v14
	s_nop 0
	v_fma_f32 v16, -v14, v15, 1.0
	v_fmac_f32_e32 v15, v16, v15
	v_div_scale_f32 v16, vcc, v13, v7, v13
	v_mul_f32_e32 v17, v16, v15
	v_fma_f32 v18, -v14, v17, v16
	v_fmac_f32_e32 v17, v18, v15
	v_fma_f32 v14, -v14, v17, v16
	v_div_fmas_f32 v14, v14, v15, v17
	v_div_fixup_f32 v7, v14, v7, v13
	v_div_scale_f32 v13, s[0:1], v6, v6, v12
	v_rcp_f32_e32 v14, v13
	s_nop 0
	v_fma_f32 v15, -v13, v14, 1.0
	v_fmac_f32_e32 v14, v15, v14
	v_div_scale_f32 v15, vcc, v12, v6, v12
	v_mul_f32_e32 v16, v15, v14
	v_fma_f32 v17, -v13, v16, v15
	v_fmac_f32_e32 v16, v17, v14
	v_fma_f32 v13, -v13, v16, v15
	v_div_fmas_f32 v13, v13, v14, v16
	v_div_fixup_f32 v6, v13, v6, v12
	v_pk_mul_f32 v[6:7], v[10:11], v[6:7]
	v_pk_mul_f32 v[10:11], v[24:25], v[0:1] op_sel_hi:[1,0]
	v_cvt_pk_bf16_f32 v9, v6, v7
	global_load_dwordx2 v[6:7], v[4:5], off offset:96
	s_waitcnt vmcnt(0)
	v_lshlrev_b32_e32 v12, 16, v6
	global_load_dwordx2 v[4:5], v[4:5], off offset:112
	v_and_b32_e32 v6, 0xffff0000, v6
	global_store_dwordx2 v[2:3], v[8:9], off offset:80
	v_mul_f32_e32 v8, 0xbfb8aa3b, v12
	v_mul_f32_e32 v9, 0xbfb8aa3b, v6
	v_exp_f32_e32 v8, v8
	v_exp_f32_e32 v9, v9
	s_nop 0
	v_pk_add_f32 v[8:9], v[8:9], 1.0 op_sel_hi:[1,0]
	s_nop 0
	v_div_scale_f32 v13, s[0:1], v9, v9, v6
	v_rcp_f32_e32 v14, v13
	s_nop 0
	v_fma_f32 v15, -v13, v14, 1.0
	v_fmac_f32_e32 v14, v15, v14
	v_div_scale_f32 v15, vcc, v6, v9, v6
	v_mul_f32_e32 v16, v15, v14
	v_fma_f32 v17, -v13, v16, v15
	v_fmac_f32_e32 v16, v17, v14
	v_fma_f32 v13, -v13, v16, v15
	v_div_fmas_f32 v13, v13, v14, v16
	v_div_fixup_f32 v9, v13, v9, v6
	v_div_scale_f32 v6, s[0:1], v8, v8, v12
	v_rcp_f32_e32 v13, v6
	s_nop 0
	v_fma_f32 v14, -v6, v13, 1.0
	v_fmac_f32_e32 v13, v14, v13
	v_div_scale_f32 v14, vcc, v12, v8, v12
	v_mul_f32_e32 v15, v14, v13
	v_fma_f32 v16, -v6, v15, v14
	v_fmac_f32_e32 v15, v16, v13
	v_fma_f32 v6, -v6, v15, v14
	v_div_fmas_f32 v6, v6, v13, v15
	v_div_fixup_f32 v8, v6, v8, v12
	v_lshlrev_b32_e32 v12, 16, v7
	v_and_b32_e32 v13, 0xffff0000, v7
	v_mul_f32_e32 v6, 0xbfb8aa3b, v12
	v_mul_f32_e32 v7, 0xbfb8aa3b, v13
	v_exp_f32_e32 v6, v6
	v_exp_f32_e32 v7, v7
	v_pk_mul_f32 v[8:9], v[10:11], v[8:9]
	v_pk_mul_f32 v[10:11], v[26:27], v[0:1] op_sel_hi:[1,0]
	v_cvt_pk_bf16_f32 v8, v8, v9
	v_pk_add_f32 v[6:7], v[6:7], 1.0 op_sel_hi:[1,0]
	s_nop 0
	v_div_scale_f32 v14, s[0:1], v7, v7, v13
	v_rcp_f32_e32 v15, v14
	s_nop 0
	v_fma_f32 v16, -v14, v15, 1.0
	v_fmac_f32_e32 v15, v16, v15
	v_div_scale_f32 v16, vcc, v13, v7, v13
	v_mul_f32_e32 v17, v16, v15
	v_fma_f32 v18, -v14, v17, v16
	v_fmac_f32_e32 v17, v18, v15
	v_fma_f32 v14, -v14, v17, v16
	v_div_fmas_f32 v14, v14, v15, v17
	v_div_fixup_f32 v7, v14, v7, v13
	v_div_scale_f32 v13, s[0:1], v6, v6, v12
	v_rcp_f32_e32 v14, v13
	s_nop 0
	v_fma_f32 v15, -v13, v14, 1.0
	v_fmac_f32_e32 v14, v15, v14
	v_div_scale_f32 v15, vcc, v12, v6, v12
	v_mul_f32_e32 v16, v15, v14
	v_fma_f32 v17, -v13, v16, v15
	v_fmac_f32_e32 v16, v17, v14
	v_fma_f32 v13, -v13, v16, v15
	v_div_fmas_f32 v13, v13, v14, v16
	v_div_fixup_f32 v6, v13, v6, v12
	v_pk_mul_f32 v[6:7], v[10:11], v[6:7]
	s_waitcnt vmcnt(1)
	v_lshlrev_b32_e32 v10, 16, v4
	v_and_b32_e32 v4, 0xffff0000, v4
	v_cvt_pk_bf16_f32 v9, v6, v7
	v_mul_f32_e32 v6, 0xbfb8aa3b, v10
	v_mul_f32_e32 v7, 0xbfb8aa3b, v4
	v_exp_f32_e32 v6, v6
	v_exp_f32_e32 v7, v7
	global_store_dwordx2 v[2:3], v[8:9], off offset:96
	v_pk_mul_f32 v[8:9], v[28:29], v[0:1] op_sel_hi:[1,0]
	v_pk_add_f32 v[6:7], v[6:7], 1.0 op_sel_hi:[1,0]
	s_nop 0
	v_div_scale_f32 v11, s[0:1], v7, v7, v4
	v_rcp_f32_e32 v12, v11
	s_nop 0
	v_fma_f32 v13, -v11, v12, 1.0
	v_fmac_f32_e32 v12, v13, v12
	v_div_scale_f32 v13, vcc, v4, v7, v4
	v_mul_f32_e32 v14, v13, v12
	v_fma_f32 v15, -v11, v14, v13
	v_fmac_f32_e32 v14, v15, v12
	v_fma_f32 v11, -v11, v14, v13
	v_div_fmas_f32 v11, v11, v12, v14
	v_div_fixup_f32 v7, v11, v7, v4
	v_div_scale_f32 v4, s[0:1], v6, v6, v10
	v_rcp_f32_e32 v11, v4
	s_nop 0
	v_fma_f32 v12, -v4, v11, 1.0
	v_fmac_f32_e32 v11, v12, v11
	v_div_scale_f32 v12, vcc, v10, v6, v10
	v_mul_f32_e32 v13, v12, v11
	v_fma_f32 v14, -v4, v13, v12
	v_fmac_f32_e32 v13, v14, v11
	v_fma_f32 v4, -v4, v13, v12
	v_div_fmas_f32 v4, v4, v11, v13
	v_div_fixup_f32 v6, v4, v6, v10
	v_lshlrev_b32_e32 v10, 16, v5
	v_and_b32_e32 v11, 0xffff0000, v5
	v_pk_mul_f32 v[6:7], v[8:9], v[6:7]
	v_mul_f32_e32 v4, 0xbfb8aa3b, v10
	v_pk_mul_f32 v[8:9], v[30:31], v[0:1] op_sel_hi:[1,0]
	v_mul_f32_e32 v0, 0xbfb8aa3b, v11
	v_exp_f32_e32 v4, v4
	v_exp_f32_e32 v5, v0
	v_cvt_pk_bf16_f32 v6, v6, v7
	v_pk_add_f32 v[4:5], v[4:5], 1.0 op_sel_hi:[1,0]
	s_nop 0
	v_div_scale_f32 v0, s[0:1], v5, v5, v11
	v_rcp_f32_e32 v12, v0
	s_nop 0
	v_fma_f32 v13, -v0, v12, 1.0
	v_fmac_f32_e32 v12, v13, v12
	v_div_scale_f32 v13, vcc, v11, v5, v11
	v_mul_f32_e32 v14, v13, v12
	v_fma_f32 v15, -v0, v14, v13
	v_fmac_f32_e32 v14, v15, v12
	v_fma_f32 v0, -v0, v14, v13
	v_div_fmas_f32 v0, v0, v12, v14
	v_div_fixup_f32 v5, v0, v5, v11
	v_div_scale_f32 v0, s[0:1], v4, v4, v10
	v_rcp_f32_e32 v11, v0
	s_nop 0
	v_fma_f32 v12, -v0, v11, 1.0
	v_fmac_f32_e32 v11, v12, v11
	v_div_scale_f32 v12, vcc, v10, v4, v10
	v_mul_f32_e32 v13, v12, v11
	v_fma_f32 v14, -v0, v13, v12
	v_fmac_f32_e32 v13, v14, v11
	v_fma_f32 v0, -v0, v13, v12
	v_div_fmas_f32 v0, v0, v11, v13
	v_div_fixup_f32 v4, v0, v4, v10
	v_pk_mul_f32 v[4:5], v[8:9], v[4:5]
	s_nop 0
	v_cvt_pk_bf16_f32 v7, v4, v5
	global_store_dwordx2 v[2:3], v[6:7], off offset:112

.LBB0_744:
	s_and_b64 vcc, exec, s[0:1]
	s_cbranch_vccz .LBB0_739
	s_bfe_u32 s0, s5, 0x30003
	v_mov_b32_e32 v29, v193
	s_lshl_b32 s0, s0, 8
	s_ashr_i32 s3, s5, 6
	v_and_b32_e32 v0, 0xffffffc0, v29
	v_and_b32_e32 v30, 31, v29
	v_add_u32_e32 v0, s0, v0
	s_and_b32 s8, s5, 7
	s_lshl_b32 s1, s3, 3
	v_or_b32_e32 v188, v0, v30
	s_or_b32 s13, s1, s8
	v_ashrrev_i32_e32 v189, 31, v188
	v_mad_i64_i32 v[2:3], s[0:1], s13, v198, v[188:189]
	v_mov_b64_e32 v[4:5], s[40:41]
	s_movk_i32 s6, 0xc0
	v_bfe_u32 v31, v29, 5, 1
	v_mad_u64_u32 v[4:5], s[0:1], v2, s6, v[4:5]
	v_lshlrev_b32_e32 v0, 4, v31
	v_mad_i32_i24 v5, v3, s6, v5
	v_lshl_add_u64 v[26:27], v[4:5], 0, v[0:1]
	s_mov_b64 s[0:1], 0x1800
	v_lshl_add_u64 v[22:23], v[26:27], 0, s[0:1]
	s_movk_i32 s0, 0x1000
	v_add_co_u32_e32 v2, vcc, s0, v26
	s_nop 1
	v_addc_co_u32_e32 v3, vcc, 0, v27, vcc
	s_barrier
	global_load_dwordx4 v[2:5], v[2:3], off offset:2048
	s_nop 0
	global_load_dwordx4 v[6:9], v[22:23], off offset:32
	global_load_dwordx4 v[10:13], v[22:23], off offset:64
	global_load_dwordx4 v[14:17], v[22:23], off offset:96
	global_load_dwordx4 v[18:21], v[22:23], off offset:128
	s_nop 0
	global_load_dwordx4 v[22:25], v[22:23], off offset:160
	v_lshrrev_b32_e32 v29, 1, v29
	s_mov_b32 s0, 0xfffffe0
	v_and_or_b32 v29, v29, s0, v30
	s_mul_i32 s9, s13, 0x6c000
	v_add_u32_e32 v192, 0, v0
	v_readlane_b32 s0, v254, 7
	s_movk_i32 s16, 0xd0
	s_add_u32 s6, s0, s9
	v_mad_u64_u32 v[194:195], s[0:1], v29, s16, v[192:193]
	s_mul_hi_i32 s10, s13, 0x6c000
	v_readlane_b32 s0, v254, 8
	v_mov_b32_e32 v28, v193
	s_mul_hi_i32 s12, s13, 0x48000
	s_mul_i32 s13, s13, 0x48000
	s_addc_u32 s7, s0, s10
	v_readlane_b32 s0, v254, 9
	s_add_u32 s0, s0, s13
	v_readlane_b32 s1, v254, 10
	global_load_dwordx4 v[144:147], v[26:27], off
	global_load_dwordx4 v[148:151], v[26:27], off offset:32
	global_load_dwordx4 v[152:155], v[26:27], off offset:64
	global_load_dwordx4 v[156:159], v[26:27], off offset:96
	global_load_dwordx4 v[160:163], v[26:27], off offset:128
	global_load_dwordx4 v[164:167], v[26:27], off offset:160
	s_addc_u32 s1, s1, s12
	s_movk_i32 s17, 0x2000
	s_movk_i32 s11, 0x1200
	v_lshlrev_b32_e32 v190, 3, v31
	v_mul_u32_u24_e32 v191, 0xd0, v30
	v_mov_b32_e32 v215, 0xf149f2ca
	v_mov_b32_e32 v195, 0
	s_waitcnt vmcnt(11)
	ds_write_b128 v194, v[2:5] offset:47104
	s_waitcnt vmcnt(10)
	ds_write_b128 v194, v[6:9] offset:47136
	s_waitcnt vmcnt(9)
	ds_write_b128 v194, v[10:13] offset:47168
	s_waitcnt vmcnt(8)
	ds_write_b128 v194, v[14:17] offset:47200
	s_waitcnt vmcnt(7)
	ds_write_b128 v194, v[18:21] offset:47232
	s_waitcnt vmcnt(6)
	ds_write_b128 v194, v[22:25] offset:47264
	v_mov_b32_e32 v23, v193
	v_ashrrev_i32_e32 v29, 31, v28
	v_lshlrev_b32_e32 v0, 4, v28
	v_add_u32_e32 v2, 0x100, v28
	v_lshl_add_u64 v[4:5], v[28:29], 4, s[6:7]
	v_and_b32_e32 v0, 0x70, v0
	v_ashrrev_i32_e32 v14, 3, v28
	v_ashrrev_i32_e32 v3, 31, v2
	v_ashrrev_i32_e32 v16, 3, v2
	v_add_co_u32_e32 v10, vcc, s17, v4
	v_lshl_add_u64 v[12:13], s[0:1], 0, v[0:1]
	v_lshl_add_u64 v[6:7], v[2:3], 4, s[6:7]
	v_addc_co_u32_e32 v11, vcc, 0, v5, vcc
	v_mad_i64_i32 v[14:15], s[14:15], v14, s11, v[12:13]
	v_mad_i64_i32 v[18:19], s[14:15], v16, s11, v[12:13]
	global_load_dwordx4 v[2:5], v[4:5], off
	s_nop 0
	global_load_dwordx4 v[6:9], v[6:7], off
	s_nop 0
	global_load_dwordx4 v[10:13], v[10:11], off
	s_nop 0
	global_load_dwordx4 v[14:17], v[14:15], off
	s_nop 0
	global_load_dwordx4 v[18:21], v[18:19], off
	s_mov_b32 s14, 0x2aaaaaab
	v_mov_b32_e32 v22, v193
	v_mul_hi_i32 v0, v23, s14
	v_add_u32_e32 v28, 0x100, v23
	v_add_u32_e32 v29, 0x200, v23
	v_lshlrev_b32_e32 v24, 4, v23
	v_lshrrev_b32_e32 v26, 31, v0
	v_ashrrev_i32_e32 v0, 1, v0
	v_mul_hi_i32 v27, v28, s14
	v_mul_hi_i32 v32, v29, s14
	v_and_b32_e32 v24, 0x70, v24
	v_add_u32_e32 v26, v0, v26
	v_lshrrev_b32_e32 v34, 31, v27
	v_ashrrev_i32_e32 v27, 1, v27
	v_lshrrev_b32_e32 v25, 3, v23
	v_lshrrev_b32_e32 v33, 3, v28
	v_lshrrev_b32_e32 v35, 31, v32
	v_ashrrev_i32_e32 v32, 1, v32
	v_add_u32_e32 v0, 0, v24
	v_mul_lo_u32 v36, v26, 12
	v_add_u32_e32 v34, v27, v34
	v_mul_lo_u32 v37, v26, s16
	v_add_u32_e32 v32, v32, v35
	v_mad_u64_u32 v[24:25], s[14:15], v25, s91, v[0:1]
	v_mad_u64_u32 v[26:27], s[14:15], v33, s91, v[0:1]
	v_sub_u32_e32 v0, v23, v36
	v_mul_lo_u32 v23, v34, 12
	v_mul_lo_u32 v27, v32, 12
	v_sub_u32_e32 v23, v28, v23
	v_mul_lo_u32 v25, v34, s16
	v_lshlrev_b32_e32 v0, 4, v0
	v_sub_u32_e32 v27, v29, v27
	v_lshlrev_b32_e32 v23, 4, v23
	s_add_u32 s6, s6, 0x3000
	v_mul_lo_u32 v32, v32, s16
	v_add3_u32 v0, 0, v37, v0
	v_lshlrev_b32_e32 v27, 4, v27
	v_add3_u32 v23, 0, v25, v23
	s_addc_u32 s7, s7, 0
	v_add3_u32 v25, 0, v32, v27
	s_waitcnt vmcnt(4)
	ds_write_b128 v0, v[2:5]
	s_waitcnt vmcnt(3)
	ds_write_b128 v23, v[6:9]
	s_waitcnt vmcnt(2)
	ds_write_b128 v25, v[10:13]
	s_waitcnt vmcnt(1)
	ds_write_b128 v24, v[14:17] offset:13312
	s_waitcnt vmcnt(0)
	ds_write_b128 v26, v[18:21] offset:13312
	v_mov_b32_e32 v204, v0
	v_mov_b32_e32 v205, v23
	v_mov_b32_e32 v209, v25
	v_mov_b32_e32 v212, v24
	v_mov_b32_e32 v235, v26
	v_mov_b32_e32 v14, v1
	v_ashrrev_i32_e32 v23, 31, v22
	v_add_u32_e32 v2, 0x100, v22
	v_lshlrev_b32_e32 v0, 4, v22
	v_lshl_add_u64 v[4:5], v[22:23], 4, s[6:7]
	v_ashrrev_i32_e32 v3, 31, v2
	v_and_b32_e32 v0, 0x70, v0
	v_add_co_u32_e32 v6, vcc, s17, v4
	v_ashrrev_i32_e32 v10, 3, v22
	v_ashrrev_i32_e32 v11, 3, v2
	v_lshl_add_u64 v[2:3], v[2:3], 4, s[6:7]
	v_addc_co_u32_e32 v7, vcc, 0, v5, vcc
	v_lshl_add_u64 v[8:9], s[0:1], 0, v[0:1]
	global_load_dwordx4 v[168:171], v[4:5], off
	global_load_dwordx4 v[172:175], v[2:3], off
	v_mad_i64_i32 v[2:3], s[0:1], v10, s11, v[8:9]
	v_mad_i64_i32 v[4:5], s[0:1], v11, s11, v[8:9]
	global_load_dwordx4 v[176:179], v[6:7], off
	global_load_dwordx4 v[180:183], v[2:3], off offset:128
	global_load_dwordx4 v[184:187], v[4:5], off offset:128
	v_and_b32_e32 v2, 64, v200
	v_xor_b32_e32 v0, 32, v200
	v_add_u32_e32 v2, 64, v2
	v_cmp_lt_i32_e32 vcc, v0, v2
	v_readlane_b32 s0, v255, 23
	s_add_u32 s9, s0, s9
	v_cndmask_b32_e32 v0, v200, v0, vcc
	v_readlane_b32 s0, v255, 24
	v_lshlrev_b32_e32 v189, 2, v0
	v_sub_u32_e32 v0, v192, v190
	v_mul_u32_u24_e32 v2, 0x48, v30
	s_addc_u32 s10, s0, s10
	v_readlane_b32 s0, v255, 25
	v_mov_b32_e32 v15, v1
	v_lshl_add_u32 v214, v2, 1, v0
	s_add_u32 s0, s0, s13
	v_readlane_b32 s1, v255, 26
	v_mov_b32_e32 v0, v1
	v_mov_b32_e32 v2, v1
	v_mov_b32_e32 v3, v1
	v_mov_b32_e32 v4, v1
	v_mov_b32_e32 v5, v1
	v_mov_b32_e32 v6, v1
	v_mov_b32_e32 v7, v1
	v_mov_b32_e32 v8, v1
	v_mov_b32_e32 v9, v1
	v_mov_b32_e32 v10, v1
	v_mov_b32_e32 v11, v1
	v_mov_b32_e32 v12, v1
	v_mov_b32_e32 v13, v1
	v_mov_b64_e32 v[30:31], v[14:15]
	v_mov_b64_e32 v[46:47], v[14:15]
	v_mov_b64_e32 v[62:63], v[14:15]
	v_mov_b64_e32 v[78:79], v[14:15]
	s_movk_i32 s16, 0x2000
	s_mov_b32 s11, 0
	s_addc_u32 s1, s1, s12
	s_mov_b64 s[6:7], 0
	v_mov_b64_e32 v[28:29], v[12:13]
	v_mov_b64_e32 v[26:27], v[10:11]
	v_mov_b64_e32 v[24:25], v[8:9]
	v_mov_b64_e32 v[22:23], v[6:7]
	v_mov_b64_e32 v[20:21], v[4:5]
	v_mov_b64_e32 v[18:19], v[2:3]
	v_mov_b64_e32 v[16:17], v[0:1]
	v_mov_b64_e32 v[44:45], v[12:13]
	v_mov_b64_e32 v[42:43], v[10:11]
	v_mov_b64_e32 v[40:41], v[8:9]
	v_mov_b64_e32 v[38:39], v[6:7]
	v_mov_b64_e32 v[36:37], v[4:5]
	v_mov_b64_e32 v[34:35], v[2:3]
	v_mov_b64_e32 v[32:33], v[0:1]
	v_mov_b64_e32 v[60:61], v[12:13]
	v_mov_b64_e32 v[58:59], v[10:11]
	v_mov_b64_e32 v[56:57], v[8:9]
	v_mov_b64_e32 v[54:55], v[6:7]
	v_mov_b64_e32 v[52:53], v[4:5]
	v_mov_b64_e32 v[50:51], v[2:3]
	v_mov_b64_e32 v[48:49], v[0:1]
	v_mov_b64_e32 v[76:77], v[12:13]
	v_mov_b64_e32 v[74:75], v[10:11]
	v_mov_b64_e32 v[72:73], v[8:9]
	v_mov_b64_e32 v[70:71], v[6:7]
	v_mov_b64_e32 v[68:69], v[4:5]
	v_mov_b64_e32 v[66:67], v[2:3]
	v_mov_b64_e32 v[64:65], v[0:1]
	v_mov_b32_e32 v0, 0
	v_mov_b32_e32 v14, 0xf149f2ca
	ds_read_b128 v[10:13], v194 offset:47104
	ds_read_b128 v[216:219], v194 offset:47136
	ds_read_b128 v[6:9], v194 offset:47168
	ds_read_b128 v[220:223], v194 offset:47200
	ds_read_b128 v[224:227], v194 offset:47232
	ds_read_b128 v[228:231], v194 offset:47264
	s_waitcnt lgkmcnt(6)
	s_barrier
.LBB0_746:
	s_bitcmp1_b32 s11, 0
	s_cselect_b32 s12, 0x2c00, 0
	s_lshl_b32 s13, s12, 1
	v_add3_u32 v15, v192, s13, v191
	ds_read_b128 v[2:5], v15
	ds_read_b128 v[240:243], v15 offset:32
	ds_read_b128 v[244:247], v15 offset:64
	ds_read_b128 v[248:251], v15 offset:96
	s_waitcnt lgkmcnt(3)
	v_mfma_f32_32x32x16_bf16 v[112:127], v[2:5], v[144:147], 0
	v_mfma_f32_32x32x16_bf16 v[96:111], v[2:5], v[10:13], 0
	ds_read_b128 v[2:5], v15 offset:128
	s_waitcnt lgkmcnt(3)
	v_mfma_f32_32x32x16_bf16 v[112:127], v[240:243], v[148:151], v[112:127]
	v_mfma_f32_32x32x16_bf16 v[96:111], v[240:243], v[216:219], v[96:111]
	ds_read_b128 v[240:243], v15 offset:160
	s_waitcnt lgkmcnt(3)
	v_mfma_f32_32x32x16_bf16 v[112:127], v[244:247], v[152:155], v[112:127]
	v_mfma_f32_32x32x16_bf16 v[96:111], v[244:247], v[6:9], v[96:111]
	ds_read_b128 v[244:247], v15 offset:6656
	s_waitcnt lgkmcnt(3)
	v_mfma_f32_32x32x16_bf16 v[112:127], v[248:251], v[156:159], v[112:127]
	v_mfma_f32_32x32x16_bf16 v[96:111], v[248:251], v[220:223], v[96:111]
	ds_read_b128 v[248:251], v15 offset:6688
	s_waitcnt lgkmcnt(3)
	v_mfma_f32_32x32x16_bf16 v[112:127], v[2:5], v[160:163], v[112:127]
	v_mfma_f32_32x32x16_bf16 v[96:111], v[2:5], v[224:227], v[96:111]
	ds_read_b128 v[2:5], v15 offset:6720
	s_waitcnt lgkmcnt(3)
	v_mfma_f32_32x32x16_bf16 v[112:127], v[240:243], v[164:167], v[112:127]
	v_mfma_f32_32x32x16_bf16 v[96:111], v[240:243], v[228:231], v[96:111]
	ds_read_b128 v[240:243], v15 offset:6752
	s_waitcnt lgkmcnt(3)
	v_mfma_f32_32x32x16_bf16 v[128:143], v[244:247], v[144:147], 0
	v_mfma_f32_32x32x16_bf16 v[80:95], v[244:247], v[10:13], 0
	ds_read_b128 v[244:247], v15 offset:6784
	s_waitcnt lgkmcnt(3)
	v_mfma_f32_32x32x16_bf16 v[128:143], v[248:251], v[148:151], v[128:143]
	v_mfma_f32_32x32x16_bf16 v[80:95], v[248:251], v[216:219], v[80:95]
	ds_read_b128 v[248:251], v15 offset:6816
	s_waitcnt lgkmcnt(3)
	v_mfma_f32_32x32x16_bf16 v[128:143], v[2:5], v[152:155], v[128:143]
	v_mfma_f32_32x32x16_bf16 v[80:95], v[2:5], v[6:9], v[80:95]
	s_waitcnt lgkmcnt(2)
	v_mfma_f32_32x32x16_bf16 v[128:143], v[240:243], v[156:159], v[128:143]
	v_mfma_f32_32x32x16_bf16 v[80:95], v[240:243], v[220:223], v[80:95]
	s_waitcnt lgkmcnt(1)
	v_mfma_f32_32x32x16_bf16 v[128:143], v[244:247], v[160:163], v[128:143]
	v_mfma_f32_32x32x16_bf16 v[80:95], v[244:247], v[224:227], v[80:95]
	s_waitcnt lgkmcnt(0)
	v_mfma_f32_32x32x16_bf16 v[128:143], v[248:251], v[164:167], v[128:143]
	v_mfma_f32_32x32x16_bf16 v[80:95], v[248:251], v[228:231], v[80:95]
	v_max_f32_e32 v2, v113, v113
	v_max_f32_e32 v3, v112, v112
	v_max_f32_e32 v2, v3, v2
	v_max3_f32 v2, v2, v114, v115
	v_max3_f32 v2, v2, v116, v117
	v_max3_f32 v2, v2, v118, v119
	v_max3_f32 v2, v2, v120, v121
	v_max3_f32 v2, v2, v122, v123
	v_max3_f32 v2, v2, v124, v125
	v_max3_f32 v2, v2, v126, v127
	s_nop 0
	v_max3_f32 v2, v2, v128, v129
	v_max3_f32 v2, v2, v130, v131
	v_max3_f32 v2, v2, v132, v133
	v_max3_f32 v2, v2, v134, v135
	v_max3_f32 v2, v2, v136, v137
	v_max3_f32 v2, v2, v138, v139
	v_max3_f32 v2, v2, v140, v141
	v_max3_f32 v2, v2, v142, v143
	v_mov_b32_e32 v3, v2
	s_nop 1
	v_permlane32_swap_b32_e32 v2, v3
	v_max_f32_e32 v3, v3, v3
	v_max_f32_e32 v2, v2, v3
	v_add_f32_e32 v3, 0xc1000000, v2
	v_cmp_gt_f32_e32 vcc, v3, v215
	s_cbranch_vccz .LBB0_748
	v_max_f32_e32 v2, v2, v2
	v_max_f32_e32 v3, v215, v215
	v_max_f32_e32 v3, v3, v2
	v_sub_f32_e32 v2, v215, v3
	v_exp_f32_e32 v2, v2
	v_mov_b32_e32 v215, v3
	v_mul_f32_e32 v0, v0, v2
	v_pk_mul_f32 v[78:79], v[78:79], v[2:3] op_sel_hi:[1,0]
	v_pk_mul_f32 v[76:77], v[76:77], v[2:3] op_sel_hi:[1,0]
	v_pk_mul_f32 v[74:75], v[74:75], v[2:3] op_sel_hi:[1,0]
	v_pk_mul_f32 v[72:73], v[72:73], v[2:3] op_sel_hi:[1,0]
	v_pk_mul_f32 v[70:71], v[70:71], v[2:3] op_sel_hi:[1,0]
	v_pk_mul_f32 v[68:69], v[68:69], v[2:3] op_sel_hi:[1,0]
	v_pk_mul_f32 v[66:67], v[66:67], v[2:3] op_sel_hi:[1,0]
	v_pk_mul_f32 v[64:65], v[64:65], v[2:3] op_sel_hi:[1,0]
	v_pk_mul_f32 v[62:63], v[62:63], v[2:3] op_sel_hi:[1,0]
	v_pk_mul_f32 v[60:61], v[60:61], v[2:3] op_sel_hi:[1,0]
	v_pk_mul_f32 v[58:59], v[58:59], v[2:3] op_sel_hi:[1,0]
	v_pk_mul_f32 v[56:57], v[56:57], v[2:3] op_sel_hi:[1,0]
	v_pk_mul_f32 v[54:55], v[54:55], v[2:3] op_sel_hi:[1,0]
	v_pk_mul_f32 v[52:53], v[52:53], v[2:3] op_sel_hi:[1,0]
	v_pk_mul_f32 v[50:51], v[50:51], v[2:3] op_sel_hi:[1,0]
	v_pk_mul_f32 v[48:49], v[48:49], v[2:3] op_sel_hi:[1,0]

.LBB0_753:
	v_add_f32_e32 v84, 0, v96
	v_add_f32_e32 v85, 0, v15
	s_add_u32 s6, s6, 0x3000
	v_add_f32_e32 v84, v97, v84
	v_add_f32_e32 v85, v216, v85
	s_addc_u32 s7, s7, 0
	v_add_f32_e32 v84, v98, v84
	v_add_f32_e32 v85, v217, v85
	s_add_u32 s0, s0, 0x80
	v_add_f32_e32 v84, v99, v84
	v_add_f32_e32 v85, v218, v85
	s_addc_u32 s1, s1, 0
	v_add_f32_e32 v84, v100, v84
	v_add_f32_e32 v85, v219, v85
	v_add_f32_e32 v84, v101, v84
	v_add_f32_e32 v85, v220, v85
	v_add_f32_e32 v84, v102, v84
	v_add_f32_e32 v85, v221, v85
	v_add_f32_e32 v84, v103, v84
	v_add_f32_e32 v85, v222, v85
	v_add_f32_e32 v84, v104, v84
	v_add_f32_e32 v85, v223, v85
	v_add_f32_e32 v84, v105, v84
	v_add_f32_e32 v85, v224, v85
	v_add_f32_e32 v84, v106, v84
	v_add_f32_e32 v85, v225, v85
	v_add_f32_e32 v84, v107, v84
	v_add_f32_e32 v85, v226, v85
	v_add_f32_e32 v84, v108, v84
	v_add_f32_e32 v85, v227, v85
	v_add_f32_e32 v84, v109, v84
	v_add_f32_e32 v85, v228, v85
	v_add_f32_e32 v84, v110, v84
	v_add_f32_e32 v85, v229, v85
	v_add_f32_e32 v84, v111, v84
	v_add_f32_e32 v85, v230, v85
	v_add_f32_e32 v80, v80, v84
	v_add_f32_e32 v85, v231, v85
	v_add_f32_e32 v6, v6, v80
	v_add_f32_e32 v85, v232, v85
	v_add_f32_e32 v6, v7, v6
	v_add_f32_e32 v85, v233, v85
	v_add_f32_e32 v6, v8, v6
	v_add_f32_e32 v85, v234, v85
	v_add_f32_e32 v6, v9, v6
	v_add_f32_e32 v85, v132, v85
	v_add_f32_e32 v6, v10, v6
	v_add_f32_e32 v85, v133, v85
	v_add_f32_e32 v2, v2, v6
	v_add_f32_e32 v85, v134, v85
	v_add_f32_e32 v2, v3, v2
	v_add_f32_e32 v85, v135, v85
	v_add_f32_e32 v2, v4, v2
	v_add_f32_e32 v85, v136, v85
	v_add_f32_e32 v2, v5, v2
	v_add_f32_e32 v85, v137, v85
	v_add_f32_e32 v2, v11, v2
	v_add_f32_e32 v85, v138, v85
	v_add_f32_e32 v2, v12, v2
	v_add_f32_e32 v85, v139, v85
	v_add_f32_e32 v2, v13, v2
	v_add_f32_e32 v85, v140, v85
	v_add_f32_e32 v2, v81, v2
	v_add_f32_e32 v85, v141, v85
	v_add_f32_e32 v2, v82, v2
	v_add_f32_e32 v85, v142, v85
	v_add_f32_e32 v2, v83, v2
	v_add_f32_e32 v85, v143, v85
	v_add_f32_e32 v195, v195, v2
	v_add_f32_e32 v0, v0, v85
	s_cmp_lg_u32 s6, 0x6c000
	ds_read_b128 v[10:13], v194 offset:47104
	ds_read_b128 v[216:219], v194 offset:47136
	ds_read_b128 v[6:9], v194 offset:47168
	ds_read_b128 v[220:223], v194 offset:47200
	ds_read_b128 v[224:227], v194 offset:47232
	ds_read_b128 v[228:231], v194 offset:47264
	s_waitcnt lgkmcnt(6)
	s_barrier
	s_cbranch_scc0 .LBB0_738
	s_mov_b32 s11, s12
	s_branch .LBB0_746
